# accumulator zeroing blocks use 64-bit moves (half the VALU moves per tile)
# speedup vs baseline: 1.0355x; 1.0034x over previous
.LBB0_46:
	v_mov_b32_e32 v65, 0
	v_mov_b32_e32 v64, v65
	v_mov_b64_e32 v[2:3], v[64:65]
	v_mov_b64_e32 v[4:5], v[64:65]
	v_mov_b64_e32 v[6:7], v[64:65]
	v_mov_b64_e32 v[8:9], v[64:65]
	v_mov_b64_e32 v[10:11], v[64:65]
	v_mov_b64_e32 v[12:13], v[64:65]
	v_mov_b64_e32 v[14:15], v[64:65]
	v_mov_b64_e32 v[16:17], v[64:65]
	v_mov_b64_e32 v[18:19], v[64:65]
	v_mov_b64_e32 v[20:21], v[64:65]
	v_mov_b64_e32 v[22:23], v[64:65]
	v_mov_b64_e32 v[24:25], v[64:65]
	v_mov_b64_e32 v[26:27], v[64:65]
	v_mov_b64_e32 v[28:29], v[64:65]
	v_mov_b64_e32 v[30:31], v[64:65]
	v_mov_b64_e32 v[32:33], v[64:65]
	v_mov_b64_e32 v[34:35], v[64:65]
	v_mov_b64_e32 v[36:37], v[64:65]
	v_mov_b64_e32 v[38:39], v[64:65]
	v_mov_b64_e32 v[40:41], v[64:65]
	v_mov_b64_e32 v[42:43], v[64:65]
	v_mov_b64_e32 v[44:45], v[64:65]
	v_mov_b64_e32 v[46:47], v[64:65]
	v_mov_b64_e32 v[48:49], v[64:65]
	v_mov_b64_e32 v[50:51], v[64:65]
	v_mov_b64_e32 v[52:53], v[64:65]
	v_mov_b64_e32 v[54:55], v[64:65]
	v_mov_b64_e32 v[56:57], v[64:65]
	v_mov_b64_e32 v[58:59], v[64:65]
	v_mov_b64_e32 v[60:61], v[64:65]
	v_mov_b64_e32 v[62:63], v[64:65]

.LBB0_54:
	s_waitcnt lgkmcnt(0)
	s_barrier
	s_cmp_lt_i32 s18, 1
	s_cbranch_scc1 .LBB0_46
	v_and_b32_e32 v0, 0x5f, v10
	v_mul_u32_u24_e32 v137, 0x90, v0
	v_lshrrev_b32_e32 v0, 1, v10
	v_and_b32_e32 v2, 31, v10
	v_and_b32_e32 v138, 16, v0
	v_and_or_b32 v0, v0, s88, v2
	v_mov_b32_e32 v2, 0
	v_mul_lo_u32 v139, v0, s87
	v_or_b32_e32 v0, 0x80, v11
	s_mov_b32 s19, 0
	v_mov_b32_e32 v3, v2
	v_mov_b64_e32 v[4:5], v[2:3]
	v_mov_b64_e32 v[6:7], v[2:3]
	v_mov_b64_e32 v[8:9], v[2:3]
	v_mov_b64_e32 v[10:11], v[2:3]
	v_mov_b64_e32 v[12:13], v[2:3]
	v_mov_b64_e32 v[14:15], v[2:3]
	v_mov_b64_e32 v[16:17], v[2:3]
	v_mov_b64_e32 v[18:19], v[2:3]
	v_mov_b64_e32 v[20:21], v[2:3]
	v_mov_b64_e32 v[22:23], v[2:3]
	v_mov_b64_e32 v[24:25], v[2:3]
	v_mov_b64_e32 v[26:27], v[2:3]
	v_mov_b64_e32 v[28:29], v[2:3]
	v_mov_b64_e32 v[30:31], v[2:3]
	v_mov_b64_e32 v[32:33], v[2:3]
	v_mov_b64_e32 v[34:35], v[2:3]
	v_mov_b64_e32 v[36:37], v[2:3]
	v_mov_b64_e32 v[38:39], v[2:3]
	v_mov_b64_e32 v[40:41], v[2:3]
	v_mov_b64_e32 v[42:43], v[2:3]
	v_mov_b64_e32 v[44:45], v[2:3]
	v_mov_b64_e32 v[46:47], v[2:3]
	v_mov_b64_e32 v[48:49], v[2:3]
	v_mov_b64_e32 v[50:51], v[2:3]
	v_mov_b64_e32 v[52:53], v[2:3]
	v_mov_b64_e32 v[54:55], v[2:3]
	v_mov_b64_e32 v[56:57], v[2:3]
	v_mov_b64_e32 v[58:59], v[2:3]
	v_mov_b64_e32 v[60:61], v[2:3]
	v_mov_b64_e32 v[62:63], v[2:3]
	v_mov_b64_e32 v[64:65], v[2:3]

.LBB0_77:
	v_mov_b32_e32 v129, 0
	v_mov_b32_e32 v128, v129
	v_mov_b64_e32 v[2:3], v[128:129]
	v_mov_b64_e32 v[4:5], v[128:129]
	v_mov_b64_e32 v[6:7], v[128:129]
	v_mov_b64_e32 v[8:9], v[128:129]
	v_mov_b64_e32 v[10:11], v[128:129]
	v_mov_b64_e32 v[12:13], v[128:129]
	v_mov_b64_e32 v[14:15], v[128:129]
	v_mov_b64_e32 v[16:17], v[128:129]
	v_mov_b64_e32 v[18:19], v[128:129]
	v_mov_b64_e32 v[20:21], v[128:129]
	v_mov_b64_e32 v[22:23], v[128:129]
	v_mov_b64_e32 v[24:25], v[128:129]
	v_mov_b64_e32 v[26:27], v[128:129]
	v_mov_b64_e32 v[28:29], v[128:129]
	v_mov_b64_e32 v[30:31], v[128:129]
	v_mov_b64_e32 v[32:33], v[128:129]
	v_mov_b64_e32 v[34:35], v[128:129]
	v_mov_b64_e32 v[36:37], v[128:129]
	v_mov_b64_e32 v[38:39], v[128:129]
	v_mov_b64_e32 v[40:41], v[128:129]
	v_mov_b64_e32 v[42:43], v[128:129]
	v_mov_b64_e32 v[44:45], v[128:129]
	v_mov_b64_e32 v[46:47], v[128:129]
	v_mov_b64_e32 v[48:49], v[128:129]
	v_mov_b64_e32 v[50:51], v[128:129]
	v_mov_b64_e32 v[52:53], v[128:129]
	v_mov_b64_e32 v[54:55], v[128:129]
	v_mov_b64_e32 v[56:57], v[128:129]
	v_mov_b64_e32 v[58:59], v[128:129]
	v_mov_b64_e32 v[60:61], v[128:129]
	v_mov_b64_e32 v[62:63], v[128:129]
	v_mov_b64_e32 v[64:65], v[128:129]
	v_mov_b64_e32 v[66:67], v[128:129]
	v_mov_b64_e32 v[68:69], v[128:129]
	v_mov_b64_e32 v[70:71], v[128:129]
	v_mov_b64_e32 v[72:73], v[128:129]
	v_mov_b64_e32 v[74:75], v[128:129]
	v_mov_b64_e32 v[76:77], v[128:129]
	v_mov_b64_e32 v[78:79], v[128:129]
	v_mov_b64_e32 v[80:81], v[128:129]
	v_mov_b64_e32 v[82:83], v[128:129]
	v_mov_b64_e32 v[84:85], v[128:129]
	v_mov_b64_e32 v[86:87], v[128:129]
	v_mov_b64_e32 v[88:89], v[128:129]
	v_mov_b64_e32 v[90:91], v[128:129]
	v_mov_b64_e32 v[92:93], v[128:129]
	v_mov_b64_e32 v[94:95], v[128:129]
	v_mov_b64_e32 v[96:97], v[128:129]
	v_mov_b64_e32 v[98:99], v[128:129]
	v_mov_b64_e32 v[100:101], v[128:129]
	v_mov_b64_e32 v[102:103], v[128:129]
	v_mov_b64_e32 v[104:105], v[128:129]
	v_mov_b64_e32 v[106:107], v[128:129]
	v_mov_b64_e32 v[108:109], v[128:129]
	v_mov_b64_e32 v[110:111], v[128:129]
	v_mov_b64_e32 v[112:113], v[128:129]
	v_mov_b64_e32 v[114:115], v[128:129]
	v_mov_b64_e32 v[116:117], v[128:129]
	v_mov_b64_e32 v[118:119], v[128:129]
	v_mov_b64_e32 v[120:121], v[128:129]
	v_mov_b64_e32 v[122:123], v[128:129]
	v_mov_b64_e32 v[124:125], v[128:129]
	v_mov_b64_e32 v[126:127], v[128:129]

.LBB0_85:
	s_waitcnt lgkmcnt(0)
	s_barrier
	s_cmp_lt_i32 s7, 1
	s_cbranch_scc1 .LBB0_77
	v_and_b32_e32 v0, 31, v10
	v_lshrrev_b32_e32 v2, 1, v10
	v_and_or_b32 v3, v2, s88, v0
	v_and_b32_e32 v248, 16, v2
	v_lshlrev_b32_e32 v2, 1, v10
	s_movk_i32 s9, 0x80
	v_and_or_b32 v0, v2, s9, v0
	v_mov_b32_e32 v2, 0
	v_mul_lo_u32 v247, v3, s87
	v_mul_u32_u24_e32 v249, 0x90, v0
	v_or_b32_e32 v0, 0x80, v11
	s_mov_b32 s9, 0
	v_mov_b32_e32 v3, v2
	v_mov_b64_e32 v[4:5], v[2:3]
	v_mov_b64_e32 v[6:7], v[2:3]
	v_mov_b64_e32 v[8:9], v[2:3]
	v_mov_b64_e32 v[10:11], v[2:3]
	v_mov_b64_e32 v[12:13], v[2:3]
	v_mov_b64_e32 v[14:15], v[2:3]
	v_mov_b64_e32 v[16:17], v[2:3]
	v_mov_b64_e32 v[18:19], v[2:3]
	v_mov_b64_e32 v[20:21], v[2:3]
	v_mov_b64_e32 v[22:23], v[2:3]
	v_mov_b64_e32 v[24:25], v[2:3]
	v_mov_b64_e32 v[26:27], v[2:3]
	v_mov_b64_e32 v[28:29], v[2:3]
	v_mov_b64_e32 v[30:31], v[2:3]
	v_mov_b64_e32 v[32:33], v[2:3]
	v_mov_b64_e32 v[34:35], v[2:3]
	v_mov_b64_e32 v[36:37], v[2:3]
	v_mov_b64_e32 v[38:39], v[2:3]
	v_mov_b64_e32 v[40:41], v[2:3]
	v_mov_b64_e32 v[42:43], v[2:3]
	v_mov_b64_e32 v[44:45], v[2:3]
	v_mov_b64_e32 v[46:47], v[2:3]
	v_mov_b64_e32 v[48:49], v[2:3]
	v_mov_b64_e32 v[50:51], v[2:3]
	v_mov_b64_e32 v[52:53], v[2:3]
	v_mov_b64_e32 v[54:55], v[2:3]
	v_mov_b64_e32 v[56:57], v[2:3]
	v_mov_b64_e32 v[58:59], v[2:3]
	v_mov_b64_e32 v[60:61], v[2:3]
	v_mov_b64_e32 v[62:63], v[2:3]
	v_mov_b64_e32 v[64:65], v[2:3]
	v_mov_b64_e32 v[66:67], v[2:3]
	v_mov_b64_e32 v[68:69], v[2:3]
	v_mov_b64_e32 v[70:71], v[2:3]
	v_mov_b64_e32 v[72:73], v[2:3]
	v_mov_b64_e32 v[74:75], v[2:3]
	v_mov_b64_e32 v[76:77], v[2:3]
	v_mov_b64_e32 v[78:79], v[2:3]
	v_mov_b64_e32 v[80:81], v[2:3]
	v_mov_b64_e32 v[82:83], v[2:3]
	v_mov_b64_e32 v[84:85], v[2:3]
	v_mov_b64_e32 v[86:87], v[2:3]
	v_mov_b64_e32 v[88:89], v[2:3]
	v_mov_b64_e32 v[90:91], v[2:3]
	v_mov_b64_e32 v[92:93], v[2:3]
	v_mov_b64_e32 v[94:95], v[2:3]
	v_mov_b64_e32 v[96:97], v[2:3]
	v_mov_b64_e32 v[98:99], v[2:3]
	v_mov_b64_e32 v[100:101], v[2:3]
	v_mov_b64_e32 v[102:103], v[2:3]
	v_mov_b64_e32 v[104:105], v[2:3]
	v_mov_b64_e32 v[106:107], v[2:3]
	v_mov_b64_e32 v[108:109], v[2:3]
	v_mov_b64_e32 v[110:111], v[2:3]
	v_mov_b64_e32 v[112:113], v[2:3]
	v_mov_b64_e32 v[114:115], v[2:3]
	v_mov_b64_e32 v[116:117], v[2:3]
	v_mov_b64_e32 v[118:119], v[2:3]
	v_mov_b64_e32 v[120:121], v[2:3]
	v_mov_b64_e32 v[122:123], v[2:3]
	v_mov_b64_e32 v[124:125], v[2:3]
	v_mov_b64_e32 v[126:127], v[2:3]
	v_mov_b64_e32 v[128:129], v[2:3]

.LBB0_115:
	s_waitcnt lgkmcnt(0)
	s_barrier
	s_cmp_lt_i32 s7, 1
	s_cbranch_scc1 .LBB0_107
	v_and_b32_e32 v0, 0x5f, v10
	v_mul_u32_u24_e32 v137, 0x90, v0
	v_lshrrev_b32_e32 v0, 1, v10
	v_and_b32_e32 v2, 31, v10
	v_and_b32_e32 v138, 16, v0
	v_and_or_b32 v0, v0, s88, v2
	v_mov_b32_e32 v2, 0
	v_mul_lo_u32 v139, v0, s87
	v_or_b32_e32 v0, 0x80, v11
	s_mov_b32 s21, 0
	v_mov_b32_e32 v3, v2
	v_mov_b64_e32 v[4:5], v[2:3]
	v_mov_b64_e32 v[6:7], v[2:3]
	v_mov_b64_e32 v[8:9], v[2:3]
	v_mov_b64_e32 v[10:11], v[2:3]
	v_mov_b64_e32 v[12:13], v[2:3]
	v_mov_b64_e32 v[14:15], v[2:3]
	v_mov_b64_e32 v[16:17], v[2:3]
	v_mov_b64_e32 v[18:19], v[2:3]
	v_mov_b64_e32 v[20:21], v[2:3]
	v_mov_b64_e32 v[22:23], v[2:3]
	v_mov_b64_e32 v[24:25], v[2:3]
	v_mov_b64_e32 v[26:27], v[2:3]
	v_mov_b64_e32 v[28:29], v[2:3]
	v_mov_b64_e32 v[30:31], v[2:3]
	v_mov_b64_e32 v[32:33], v[2:3]
	v_mov_b64_e32 v[34:35], v[2:3]
	v_mov_b64_e32 v[36:37], v[2:3]
	v_mov_b64_e32 v[38:39], v[2:3]
	v_mov_b64_e32 v[40:41], v[2:3]
	v_mov_b64_e32 v[42:43], v[2:3]
	v_mov_b64_e32 v[44:45], v[2:3]
	v_mov_b64_e32 v[46:47], v[2:3]
	v_mov_b64_e32 v[48:49], v[2:3]
	v_mov_b64_e32 v[50:51], v[2:3]
	v_mov_b64_e32 v[52:53], v[2:3]
	v_mov_b64_e32 v[54:55], v[2:3]
	v_mov_b64_e32 v[56:57], v[2:3]
	v_mov_b64_e32 v[58:59], v[2:3]
	v_mov_b64_e32 v[60:61], v[2:3]
	v_mov_b64_e32 v[62:63], v[2:3]
	v_mov_b64_e32 v[64:65], v[2:3]

.LBB0_138:
	s_waitcnt lgkmcnt(0)
	s_barrier
	s_cmp_lt_i32 s10, 1
	s_cbranch_scc1 .LBB0_146
	v_and_b32_e32 v0, 0x5f, v34
	v_mul_u32_u24_e32 v152, 0x90, v0
	v_lshrrev_b32_e32 v0, 1, v34
	v_and_b32_e32 v26, 31, v34
	v_and_b32_e32 v153, 16, v0
	v_and_or_b32 v0, v0, s88, v26
	v_mov_b32_e32 v66, 0
	v_mul_lo_u32 v154, v0, s87
	v_or_b32_e32 v0, 0x80, v35
	s_mov_b32 s11, 0
	v_mov_b32_e32 v67, v66
	v_mov_b64_e32 v[68:69], v[66:67]
	v_mov_b64_e32 v[70:71], v[66:67]
	v_mov_b64_e32 v[72:73], v[66:67]
	v_mov_b64_e32 v[74:75], v[66:67]
	v_mov_b64_e32 v[76:77], v[66:67]
	v_mov_b64_e32 v[78:79], v[66:67]
	v_mov_b64_e32 v[80:81], v[66:67]
	v_mov_b64_e32 v[82:83], v[66:67]
	v_mov_b64_e32 v[84:85], v[66:67]
	v_mov_b64_e32 v[86:87], v[66:67]
	v_mov_b64_e32 v[88:89], v[66:67]
	v_mov_b64_e32 v[90:91], v[66:67]
	v_mov_b64_e32 v[92:93], v[66:67]
	v_mov_b64_e32 v[94:95], v[66:67]
	v_mov_b64_e32 v[96:97], v[66:67]
	v_mov_b64_e32 v[98:99], v[66:67]
	v_mov_b64_e32 v[100:101], v[66:67]
	v_mov_b64_e32 v[102:103], v[66:67]
	v_mov_b64_e32 v[104:105], v[66:67]
	v_mov_b64_e32 v[106:107], v[66:67]
	v_mov_b64_e32 v[108:109], v[66:67]
	v_mov_b64_e32 v[110:111], v[66:67]
	v_mov_b64_e32 v[112:113], v[66:67]
	v_mov_b64_e32 v[114:115], v[66:67]
	v_mov_b64_e32 v[116:117], v[66:67]
	v_mov_b64_e32 v[118:119], v[66:67]
	v_mov_b64_e32 v[120:121], v[66:67]
	v_mov_b64_e32 v[122:123], v[66:67]
	v_mov_b64_e32 v[124:125], v[66:67]
	v_mov_b64_e32 v[126:127], v[66:67]
	v_mov_b64_e32 v[128:129], v[66:67]

.LBB0_146:
	v_mov_b32_e32 v129, 0
	v_mov_b32_e32 v128, v129
	v_mov_b64_e32 v[66:67], v[128:129]
	v_mov_b64_e32 v[68:69], v[128:129]
	v_mov_b64_e32 v[70:71], v[128:129]
	v_mov_b64_e32 v[72:73], v[128:129]
	v_mov_b64_e32 v[74:75], v[128:129]
	v_mov_b64_e32 v[76:77], v[128:129]
	v_mov_b64_e32 v[78:79], v[128:129]
	v_mov_b64_e32 v[80:81], v[128:129]
	v_mov_b64_e32 v[82:83], v[128:129]
	v_mov_b64_e32 v[84:85], v[128:129]
	v_mov_b64_e32 v[86:87], v[128:129]
	v_mov_b64_e32 v[88:89], v[128:129]
	v_mov_b64_e32 v[90:91], v[128:129]
	v_mov_b64_e32 v[92:93], v[128:129]
	v_mov_b64_e32 v[94:95], v[128:129]
	v_mov_b64_e32 v[96:97], v[128:129]
	v_mov_b64_e32 v[98:99], v[128:129]
	v_mov_b64_e32 v[100:101], v[128:129]
	v_mov_b64_e32 v[102:103], v[128:129]
	v_mov_b64_e32 v[104:105], v[128:129]
	v_mov_b64_e32 v[106:107], v[128:129]
	v_mov_b64_e32 v[108:109], v[128:129]
	v_mov_b64_e32 v[110:111], v[128:129]
	v_mov_b64_e32 v[112:113], v[128:129]
	v_mov_b64_e32 v[114:115], v[128:129]
	v_mov_b64_e32 v[116:117], v[128:129]
	v_mov_b64_e32 v[118:119], v[128:129]
	v_mov_b64_e32 v[120:121], v[128:129]
	v_mov_b64_e32 v[122:123], v[128:129]
	v_mov_b64_e32 v[124:125], v[128:129]
	v_mov_b64_e32 v[126:127], v[128:129]

.LBB0_149:
	s_waitcnt lgkmcnt(0)
	s_barrier
	s_cmp_lt_i32 s28, 1
	s_cbranch_scc1 .LBB0_134
	v_and_b32_e32 v0, 0x5f, v10
	v_mul_u32_u24_e32 v251, 0x90, v0
	v_lshrrev_b32_e32 v0, 1, v10
	v_and_b32_e32 v2, 31, v10
	v_and_b32_e32 v252, 16, v0
	v_and_or_b32 v0, v0, s88, v2
	v_mov_b32_e32 v2, 0
	v_mul_lo_u32 v243, v0, s87
	v_or_b32_e32 v0, 0x80, v11
	s_mov_b32 s29, 0
	v_mov_b32_e32 v3, v2
	v_mov_b64_e32 v[4:5], v[2:3]
	v_mov_b64_e32 v[6:7], v[2:3]
	v_mov_b64_e32 v[8:9], v[2:3]
	v_mov_b64_e32 v[10:11], v[2:3]
	v_mov_b64_e32 v[12:13], v[2:3]
	v_mov_b64_e32 v[14:15], v[2:3]
	v_mov_b64_e32 v[16:17], v[2:3]
	v_mov_b64_e32 v[18:19], v[2:3]
	v_mov_b64_e32 v[20:21], v[2:3]
	v_mov_b64_e32 v[22:23], v[2:3]
	v_mov_b64_e32 v[24:25], v[2:3]
	v_mov_b64_e32 v[26:27], v[2:3]
	v_mov_b64_e32 v[28:29], v[2:3]
	v_mov_b64_e32 v[30:31], v[2:3]
	v_mov_b64_e32 v[32:33], v[2:3]
	v_mov_b64_e32 v[34:35], v[2:3]
	v_mov_b64_e32 v[36:37], v[2:3]
	v_mov_b64_e32 v[38:39], v[2:3]
	v_mov_b64_e32 v[40:41], v[2:3]
	v_mov_b64_e32 v[42:43], v[2:3]
	v_mov_b64_e32 v[44:45], v[2:3]
	v_mov_b64_e32 v[46:47], v[2:3]
	v_mov_b64_e32 v[48:49], v[2:3]
	v_mov_b64_e32 v[50:51], v[2:3]
	v_mov_b64_e32 v[52:53], v[2:3]
	v_mov_b64_e32 v[54:55], v[2:3]
	v_mov_b64_e32 v[56:57], v[2:3]
	v_mov_b64_e32 v[58:59], v[2:3]
	v_mov_b64_e32 v[60:61], v[2:3]
	v_mov_b64_e32 v[62:63], v[2:3]
	v_mov_b64_e32 v[64:65], v[2:3]

.LBB0_189:
	s_waitcnt lgkmcnt(0)
	s_barrier
	s_cmp_lt_i32 s5, 1
	s_cbranch_scc1 .LBB0_196
	v_and_b32_e32 v0, 0x5f, v10
	v_mul_u32_u24_e32 v105, 0x90, v0
	v_lshrrev_b32_e32 v0, 1, v10
	v_and_b32_e32 v2, 31, v10
	v_and_b32_e32 v106, 16, v0
	v_and_or_b32 v0, v0, s88, v2
	v_mov_b32_e32 v2, 0
	v_mul_lo_u32 v107, v0, s87
	v_or_b32_e32 v0, 0x80, v11
	s_mov_b32 s6, 0
	v_mov_b32_e32 v3, v2
	v_mov_b64_e32 v[4:5], v[2:3]
	v_mov_b64_e32 v[6:7], v[2:3]
	v_mov_b64_e32 v[8:9], v[2:3]
	v_mov_b64_e32 v[10:11], v[2:3]
	v_mov_b64_e32 v[12:13], v[2:3]
	v_mov_b64_e32 v[14:15], v[2:3]
	v_mov_b64_e32 v[16:17], v[2:3]
	v_mov_b64_e32 v[18:19], v[2:3]
	v_mov_b64_e32 v[20:21], v[2:3]
	v_mov_b64_e32 v[22:23], v[2:3]
	v_mov_b64_e32 v[24:25], v[2:3]
	v_mov_b64_e32 v[26:27], v[2:3]
	v_mov_b64_e32 v[28:29], v[2:3]
	v_mov_b64_e32 v[30:31], v[2:3]
	v_mov_b64_e32 v[32:33], v[2:3]
	v_mov_b64_e32 v[34:35], v[2:3]
	v_mov_b64_e32 v[36:37], v[2:3]
	v_mov_b64_e32 v[38:39], v[2:3]
	v_mov_b64_e32 v[40:41], v[2:3]
	v_mov_b64_e32 v[42:43], v[2:3]
	v_mov_b64_e32 v[44:45], v[2:3]
	v_mov_b64_e32 v[46:47], v[2:3]
	v_mov_b64_e32 v[48:49], v[2:3]
	v_mov_b64_e32 v[50:51], v[2:3]
	v_mov_b64_e32 v[52:53], v[2:3]
	v_mov_b64_e32 v[54:55], v[2:3]
	v_mov_b64_e32 v[56:57], v[2:3]
	v_mov_b64_e32 v[58:59], v[2:3]
	v_mov_b64_e32 v[60:61], v[2:3]
	v_mov_b64_e32 v[62:63], v[2:3]
	v_mov_b64_e32 v[64:65], v[2:3]
	s_add_i32 s7, s6, 1
	s_cmp_ge_i32 s7, s5
	s_cbranch_scc1 .LBB0_192

.LBB0_241:
	s_or_b64 exec, exec, s[6:7]
	v_readlane_b32 s4, v254, 32
	s_add_i32 s4, s4, s3
	s_lshr_b32 s64, s4, 3
	s_lshl_b32 s8, s64, 8
	s_lshl_b32 s4, s64, 18
	v_readlane_b32 s5, v254, 57
	s_add_u32 s4, s5, s4
	v_readlane_b32 s5, v254, 31
	s_addc_u32 s5, s5, 0
	s_lshl_b32 s6, s93, 16
	s_add_u32 s6, s4, s6
	s_addc_u32 s7, s5, 0
	s_cmp_eq_u32 s2, 0
	s_cselect_b64 s[4:5], -1, 0
	s_cmp_lg_u32 s2, 0
	v_ashrrev_i32_e32 v16, 6, v98
	s_cselect_b64 s[66:67], -1, 0
	s_and_b64 s[10:11], s[4:5], exec
	v_ashrrev_i32_e32 v22, 3, v98
	v_lshrrev_b32_e32 v99, 5, v2
	v_and_b32_e32 v17, 1, v16
	s_cselect_b32 s10, 0, 0xc0
	v_add_u32_e32 v115, s8, v22
	v_ashrrev_i32_e32 v4, 2, v98
	v_lshlrev_b32_e32 v3, 5, v17
	s_movk_i32 s13, 0xffe0
	v_lshlrev_b32_e32 v19, 2, v99
	v_add_u32_e32 v6, s10, v115
	v_bfi_b32 v18, s13, v4, v98
	v_or_b32_e32 v20, v3, v19
	v_ashrrev_i32_e32 v7, 31, v6
	v_cmp_le_i32_e32 vcc, v20, v18
	s_mov_b32 s9, 0x1d558000
	v_lshlrev_b64 v[8:9], 9, v[6:7]
	v_cndmask_b32_e64 v0, 0, 1, vcc
	v_cmp_ge_i32_e32 vcc, v20, v18
	s_cselect_b32 s9, 0x8800000, s9
	v_and_b32_e32 v23, 7, v98
	v_lshl_add_u64 v[10:11], s[72:73], 0, v[8:9]
	s_lshl_b32 s38, s12, 1
	v_lshl_add_u64 v[8:9], s[90:91], 0, v[8:9]
	v_cndmask_b32_e64 v5, 0, 1, vcc
	v_lshl_add_u64 v[10:11], v[10:11], 0, s[38:39]
	v_lshlrev_b32_e32 v12, 4, v23
	v_mov_b32_e32 v13, v1
	v_lshl_add_u64 v[8:9], v[8:9], 0, s[38:39]
	v_cndmask_b32_e64 v21, v5, v0, s[4:5]
	v_lshl_add_u64 v[10:11], v[10:11], 0, v[12:13]
	v_lshl_add_u64 v[8:9], v[8:9], 0, v[12:13]
	v_ashrrev_i32_e32 v5, 31, v4
	global_load_dwordx4 v[38:41], v[10:11], off
	global_load_dwordx4 v[34:37], v[8:9], off
	v_lshlrev_b64 v[8:9], 9, v[4:5]
	v_lshl_add_u64 v[8:9], s[6:7], 0, v[8:9]
	s_lshl_b32 s6, s10, 1
	s_mov_b32 s7, s39
	v_lshl_add_u64 v[10:11], v[8:9], 0, s[6:7]
	s_lshl_b32 s6, s2, 6
	s_add_u32 s10, s72, s38
	s_addc_u32 s11, s73, 0
	v_lshlrev_b32_e32 v5, 5, v98
	v_lshlrev_b64 v[6:7], 7, v[6:7]
	v_lshl_add_u64 v[100:101], s[10:11], 0, v[12:13]
	v_writelane_b32 v254, s38, 26
	s_add_u32 s10, s90, s38
	v_and_b32_e32 v14, 0x60, v5
	v_mov_b32_e32 v15, v1
	v_lshl_add_u64 v[6:7], s[60:61], 0, v[6:7]
	s_addc_u32 s11, s91, 0
	v_and_b32_e32 v114, 31, v98
	v_lshl_add_u64 v[10:11], v[10:11], 0, v[14:15]
	v_lshl_add_u64 v[6:7], v[6:7], 0, s[6:7]
	v_lshl_add_u64 v[104:105], v[8:9], 0, v[14:15]
	s_add_u32 s6, s60, s6
	v_lshlrev_b32_e32 v9, 2, v2
	v_mul_lo_u32 v2, v22, s87
	v_lshlrev_b32_e32 v0, 3, v23
	global_load_dwordx4 v[50:53], v[10:11], off offset:16
	global_load_dwordx4 v[54:57], v[10:11], off
	s_addc_u32 s7, s61, 0
	v_add_u32_e32 v10, 0, v2
	v_or_b32_e32 v2, v3, v114
	s_waitcnt vmcnt(0)
	v_lshl_add_u64 v[106:107], s[6:7], 0, v[0:1]
	s_and_b64 s[6:7], s[4:5], exec
	v_mad_u32_u24 v11, v2, s87, 0
	v_mul_lo_u32 v2, v18, s87
	v_lshlrev_b32_e32 v116, 5, v16
	s_cselect_b32 s75, 1, -1
	s_add_i32 s6, 0, 0x11900
	v_add_u32_e32 v120, 0, v2
	v_and_b32_e32 v2, 0x60, v116
	v_add_u32_e32 v117, s6, v9
	s_and_b64 s[6:7], s[4:5], exec
	v_or_b32_e32 v3, v2, v114
	v_lshl_add_u64 v[102:103], s[10:11], 0, v[12:13]
	s_cselect_b32 s62, 0x3ffc, 0
	v_mad_u32_u24 v13, v3, s87, 0
	v_and_b32_e32 v3, 0xffffffe0, v22
	s_add_u32 s9, s78, s9
	v_mul_lo_u32 v4, v4, s87
	s_addc_u32 s10, s79, 0
	v_add_u32_e32 v3, s8, v3
	s_lshl_b32 s8, s93, 8
	v_add_u32_e32 v8, 0, v4
	v_bfi_b32 v4, s13, v22, v98
	s_add_u32 s8, s9, s8
	v_mul_lo_u32 v4, v4, s87
	v_or_b32_e32 v123, v3, v19
	s_addc_u32 s9, s10, 0
	v_lshlrev_b32_e32 v2, 1, v2
	v_mov_b32_e32 v3, v1
	v_add_u32_e32 v122, 0, v4
	v_lshl_add_u64 v[2:3], s[8:9], 0, v[2:3]
	v_lshlrev_b32_e32 v4, 1, v114
	v_mov_b32_e32 v5, v1
	v_lshl_add_u64 v[110:111], v[2:3], 0, v[4:5]
	v_lshl_add_u32 v2, v23, 5, 0
	s_movk_i32 s8, 0x104
	v_mad_u64_u32 v[112:113], s[8:9], v22, s8, v[2:3]
	s_movk_i32 s8, 0x460
	v_and_b32_e32 v5, 1, v21
	v_add_u32_e32 v113, s62, v2
	v_mad_u32_u24 v2, v23, s8, v2
	v_cmp_eq_u32_e64 s[8:9], 1, v5
	v_or_b32_e32 v5, 1, v20
	v_cmp_lt_i32_e32 vcc, v20, v18
	v_lshl_add_u64 v[6:7], v[6:7], 0, v[0:1]
	global_load_dwordx2 v[108:109], v[6:7], off
	v_cndmask_b32_e64 v15, 0, 1, vcc
	v_cmp_ge_i32_e32 vcc, v5, v18
	v_writelane_b32 v254, s39, 27
	v_lshlrev_b32_e32 v119, 4, v99
	v_cndmask_b32_e64 v5, 0, 1, vcc
	v_cndmask_b32_e64 v5, v5, v15, s[4:5]
	v_and_b32_e32 v5, 1, v5
	v_cmp_eq_u32_e64 s[10:11], 1, v5
	v_or_b32_e32 v5, 2, v20
	v_cmp_le_i32_e32 vcc, v5, v18
	s_add_i32 s62, s62, 0
	v_add_u32_e32 v6, 0, v0
	v_cndmask_b32_e64 v15, 0, 1, vcc
	v_cmp_ge_i32_e32 vcc, v5, v18
	v_or_b32_e32 v0, 2, v0
	v_add_u32_e32 v124, s62, v119
	v_cndmask_b32_e64 v5, 0, 1, vcc
	v_cndmask_b32_e64 v5, v5, v15, s[4:5]
	v_and_b32_e32 v5, 1, v5
	v_cmp_eq_u32_e64 s[12:13], 1, v5
	v_or_b32_e32 v5, 3, v20
	v_cmp_le_i32_e32 vcc, v5, v18
	s_movk_i32 s62, 0x820
	v_mad_u32_u24 v0, v0, s87, 0
	v_cndmask_b32_e64 v15, 0, 1, vcc
	v_cmp_ge_i32_e32 vcc, v5, v18
	v_lshlrev_b32_e32 v7, 6, v22
	v_lshlrev_b32_e32 v118, 1, v22
	v_cndmask_b32_e64 v5, 0, 1, vcc
	v_cndmask_b32_e64 v5, v5, v15, s[4:5]
	v_or_b32_e32 v15, 8, v20
	v_and_b32_e32 v5, 1, v5
	v_cmp_le_i32_e32 vcc, v15, v18
	v_cmp_eq_u32_e64 s[14:15], 1, v5
	v_lshl_add_u32 v5, v17, 6, v120
	v_cndmask_b32_e64 v17, 0, 1, vcc
	v_cmp_ge_i32_e32 vcc, v15, v18
	v_lshlrev_b32_e32 v121, 3, v99
	v_add_u32_e32 v3, 0x120, v0
	v_cndmask_b32_e64 v15, 0, 1, vcc
	v_cndmask_b32_e64 v15, v15, v17, s[4:5]
	v_and_b32_e32 v15, 1, v15
	v_cmp_eq_u32_e64 s[16:17], 1, v15
	v_or_b32_e32 v15, 9, v20
	v_cmp_le_i32_e32 vcc, v15, v18
	v_add_u32_e32 v4, 0x240, v0
	s_waitcnt vmcnt(0)
	v_mov_b64_e32 v[60:61], v[36:37]
	v_cndmask_b32_e64 v17, 0, 1, vcc
	v_cmp_ge_i32_e32 vcc, v15, v18
	v_mov_b64_e32 v[64:65], v[40:41]
	s_mov_b32 s74, 0
	v_cndmask_b32_e64 v15, 0, 1, vcc
	v_cndmask_b32_e64 v15, v15, v17, s[4:5]
	v_and_b32_e32 v15, 1, v15
	v_cmp_eq_u32_e64 s[18:19], 1, v15
	v_or_b32_e32 v15, 10, v20
	v_cmp_le_i32_e32 vcc, v15, v18
	v_cmp_gt_i32_e64 s[6:7], 4, v16
	v_lshl_add_u32 v127, v16, 9, 0
	v_cndmask_b32_e64 v17, 0, 1, vcc
	v_cmp_ge_i32_e32 vcc, v15, v18
	v_add_u32_e32 v129, v6, v7
	v_add_u32_e32 v130, v8, v14
	v_cndmask_b32_e64 v15, 0, 1, vcc
	v_cndmask_b32_e64 v15, v15, v17, s[4:5]
	v_and_b32_e32 v15, 1, v15
	v_cmp_eq_u32_e64 s[20:21], 1, v15
	v_or_b32_e32 v15, 11, v20
	v_cmp_le_i32_e32 vcc, v15, v18
	v_add_u32_e32 v131, v2, v118
	v_add_u32_e32 v132, v3, v118
	v_cndmask_b32_e64 v17, 0, 1, vcc
	v_cmp_ge_i32_e32 vcc, v15, v18
	v_add_u32_e32 v133, v4, v118
	v_add_u32_e32 v134, v10, v12
	v_cndmask_b32_e64 v15, 0, 1, vcc
	v_cndmask_b32_e64 v15, v15, v17, s[4:5]
	v_and_b32_e32 v15, 1, v15
	v_cmp_eq_u32_e64 s[22:23], 1, v15
	v_or_b32_e32 v15, 16, v20
	v_cmp_le_i32_e32 vcc, v15, v18
	v_add_u32_e32 v135, v11, v119
	v_add_u32_e32 v136, v5, v121
	v_cndmask_b32_e64 v17, 0, 1, vcc
	v_cmp_ge_i32_e32 vcc, v15, v18
	v_add_u32_e32 v137, v13, v119
	v_mov_b64_e32 v[58:59], v[34:35]
	v_cndmask_b32_e64 v15, 0, 1, vcc
	v_cndmask_b32_e64 v15, v15, v17, s[4:5]
	v_and_b32_e32 v15, 1, v15
	v_cmp_eq_u32_e64 s[24:25], 1, v15
	v_or_b32_e32 v15, 17, v20
	v_cmp_le_i32_e32 vcc, v15, v18
	v_mov_b64_e32 v[62:63], v[38:39]
	s_nop 0
	v_cndmask_b32_e64 v17, 0, 1, vcc
	v_cmp_ge_i32_e32 vcc, v15, v18
	s_nop 1
	v_cndmask_b32_e64 v15, 0, 1, vcc
	v_cndmask_b32_e64 v15, v15, v17, s[4:5]
	v_and_b32_e32 v15, 1, v15
	v_cmp_eq_u32_e64 s[26:27], 1, v15
	v_or_b32_e32 v15, 18, v20
	v_cmp_le_i32_e32 vcc, v15, v18
	s_nop 1
	v_cndmask_b32_e64 v17, 0, 1, vcc
	v_cmp_ge_i32_e32 vcc, v15, v18
	s_nop 1
	v_cndmask_b32_e64 v15, 0, 1, vcc
	v_cndmask_b32_e64 v15, v15, v17, s[4:5]
	v_and_b32_e32 v15, 1, v15
	v_cmp_eq_u32_e64 s[28:29], 1, v15
	v_or_b32_e32 v15, 19, v20
	v_cmp_le_i32_e32 vcc, v15, v18
	s_nop 1
	v_cndmask_b32_e64 v17, 0, 1, vcc
	v_cmp_ge_i32_e32 vcc, v15, v18
	s_nop 1
	v_cndmask_b32_e64 v15, 0, 1, vcc
	v_cndmask_b32_e64 v15, v15, v17, s[4:5]
	v_and_b32_e32 v15, 1, v15
	v_cmp_eq_u32_e64 s[30:31], 1, v15
	v_or_b32_e32 v15, 24, v20
	v_cmp_le_i32_e32 vcc, v15, v18
	s_nop 1
	v_cndmask_b32_e64 v17, 0, 1, vcc
	v_cmp_ge_i32_e32 vcc, v15, v18
	s_nop 1
	v_cndmask_b32_e64 v15, 0, 1, vcc
	v_cndmask_b32_e64 v15, v15, v17, s[4:5]
	v_and_b32_e32 v15, 1, v15
	v_cmp_eq_u32_e64 s[34:35], 1, v15
	v_or_b32_e32 v15, 25, v20
	v_cmp_le_i32_e32 vcc, v15, v18
	s_nop 1
	v_cndmask_b32_e64 v17, 0, 1, vcc
	v_cmp_ge_i32_e32 vcc, v15, v18
	s_nop 1
	v_cndmask_b32_e64 v15, 0, 1, vcc
	v_cndmask_b32_e64 v15, v15, v17, s[4:5]
	v_and_b32_e32 v15, 1, v15
	v_cmp_eq_u32_e64 s[36:37], 1, v15
	v_or_b32_e32 v15, 26, v20
	v_cmp_le_i32_e32 vcc, v15, v18
	s_nop 1
	v_cndmask_b32_e64 v17, 0, 1, vcc
	v_cmp_ge_i32_e32 vcc, v15, v18
	s_nop 1
	v_cndmask_b32_e64 v15, 0, 1, vcc
	v_cndmask_b32_e64 v15, v15, v17, s[4:5]
	v_and_b32_e32 v15, 1, v15
	v_cmp_eq_u32_e64 s[38:39], 1, v15
	v_or_b32_e32 v15, 27, v20
	v_cmp_le_i32_e32 vcc, v15, v18
	s_nop 1
	v_cndmask_b32_e64 v17, 0, 1, vcc
	v_cmp_ge_i32_e32 vcc, v15, v18
	v_mul_lo_u32 v18, v16, s62
	s_add_i32 s62, 0, 0xd800
	v_cndmask_b32_e64 v15, 0, 1, vcc
	v_cndmask_b32_e64 v15, v15, v17, s[4:5]
	v_and_b32_e32 v15, 1, v15
	v_cmp_eq_u32_e64 s[40:41], 1, v15
	v_mad_u32_u24 v15, v114, s87, 0
	v_lshlrev_b32_e32 v17, 2, v98
	v_add3_u32 v126, v18, v9, s62
	v_mov_b32_e32 v18, 0
	v_add_u32_e32 v125, 0, v17
	v_add_u32_e32 v128, s62, v17
	v_add_u32_e32 v138, v15, v119
	v_mov_b32_e32 v19, v18
	v_mov_b64_e32 v[2:3], v[18:19]
	v_mov_b64_e32 v[4:5], v[18:19]
	v_mov_b64_e32 v[6:7], v[18:19]
	v_mov_b64_e32 v[8:9], v[18:19]
	v_mov_b64_e32 v[10:11], v[18:19]
	v_mov_b64_e32 v[12:13], v[18:19]
	v_mov_b64_e32 v[14:15], v[18:19]
	v_mov_b64_e32 v[16:17], v[18:19]
	v_mov_b64_e32 v[20:21], v[18:19]
	v_mov_b64_e32 v[22:23], v[18:19]
	v_mov_b64_e32 v[24:25], v[18:19]
	v_mov_b64_e32 v[26:27], v[18:19]
	v_mov_b64_e32 v[28:29], v[18:19]
	v_mov_b64_e32 v[30:31], v[18:19]
	v_mov_b64_e32 v[32:33], v[18:19]
	s_branch .LBB0_243

.LBB0_264:
	s_waitcnt lgkmcnt(0)
	s_barrier
	s_cmp_lt_i32 s8, 1
	s_cbranch_scc1 .LBB0_272
	v_and_b32_e32 v0, 0x5f, v10
	v_mul_u32_u24_e32 v136, 0x90, v0
	v_lshrrev_b32_e32 v0, 1, v10
	v_and_b32_e32 v2, 31, v10
	v_and_b32_e32 v137, 16, v0
	v_and_or_b32 v0, v0, s88, v2
	v_mov_b32_e32 v2, 0
	v_mul_lo_u32 v138, v0, s87
	v_or_b32_e32 v0, 0x80, v11
	s_mov_b32 s9, 0
	v_mov_b32_e32 v3, v2
	v_mov_b64_e32 v[4:5], v[2:3]
	v_mov_b64_e32 v[6:7], v[2:3]
	v_mov_b64_e32 v[8:9], v[2:3]
	v_mov_b64_e32 v[10:11], v[2:3]
	v_mov_b64_e32 v[12:13], v[2:3]
	v_mov_b64_e32 v[14:15], v[2:3]
	v_mov_b64_e32 v[16:17], v[2:3]
	v_mov_b64_e32 v[18:19], v[2:3]
	v_mov_b64_e32 v[20:21], v[2:3]
	v_mov_b64_e32 v[22:23], v[2:3]
	v_mov_b64_e32 v[24:25], v[2:3]
	v_mov_b64_e32 v[26:27], v[2:3]
	v_mov_b64_e32 v[28:29], v[2:3]
	v_mov_b64_e32 v[30:31], v[2:3]
	v_mov_b64_e32 v[32:33], v[2:3]
	v_mov_b64_e32 v[34:35], v[2:3]
	v_mov_b64_e32 v[36:37], v[2:3]
	v_mov_b64_e32 v[38:39], v[2:3]
	v_mov_b64_e32 v[40:41], v[2:3]
	v_mov_b64_e32 v[42:43], v[2:3]
	v_mov_b64_e32 v[44:45], v[2:3]
	v_mov_b64_e32 v[46:47], v[2:3]
	v_mov_b64_e32 v[48:49], v[2:3]
	v_mov_b64_e32 v[50:51], v[2:3]
	v_mov_b64_e32 v[52:53], v[2:3]
	v_mov_b64_e32 v[54:55], v[2:3]
	v_mov_b64_e32 v[56:57], v[2:3]
	v_mov_b64_e32 v[58:59], v[2:3]
	v_mov_b64_e32 v[60:61], v[2:3]
	v_mov_b64_e32 v[62:63], v[2:3]
	v_mov_b64_e32 v[64:65], v[2:3]

.LBB0_272:
	v_mov_b32_e32 v17, 0
	v_mov_b32_e32 v16, v17
	v_mov_b64_e32 v[2:3], v[16:17]
	v_mov_b64_e32 v[4:5], v[16:17]
	v_mov_b64_e32 v[6:7], v[16:17]
	v_mov_b64_e32 v[8:9], v[16:17]
	v_mov_b64_e32 v[10:11], v[16:17]
	v_mov_b64_e32 v[12:13], v[16:17]
	v_mov_b64_e32 v[14:15], v[16:17]
	v_mov_b64_e32 v[18:19], v[16:17]
	v_mov_b64_e32 v[20:21], v[16:17]
	v_mov_b64_e32 v[22:23], v[16:17]
	v_mov_b64_e32 v[24:25], v[16:17]
	v_mov_b64_e32 v[26:27], v[16:17]
	v_mov_b64_e32 v[28:29], v[16:17]
	v_mov_b64_e32 v[30:31], v[16:17]
	v_mov_b64_e32 v[32:33], v[16:17]
	v_mov_b64_e32 v[34:35], v[16:17]
	v_mov_b64_e32 v[36:37], v[16:17]
	v_mov_b64_e32 v[38:39], v[16:17]
	v_mov_b64_e32 v[40:41], v[16:17]
	v_mov_b64_e32 v[42:43], v[16:17]
	v_mov_b64_e32 v[44:45], v[16:17]
	v_mov_b64_e32 v[46:47], v[16:17]
	v_mov_b64_e32 v[48:49], v[16:17]
	v_mov_b64_e32 v[50:51], v[16:17]
	v_mov_b64_e32 v[52:53], v[16:17]
	v_mov_b64_e32 v[54:55], v[16:17]
	v_mov_b64_e32 v[56:57], v[16:17]
	v_mov_b64_e32 v[58:59], v[16:17]
	v_mov_b64_e32 v[60:61], v[16:17]
	v_mov_b64_e32 v[62:63], v[16:17]
	v_mov_b64_e32 v[64:65], v[16:17]

.LBB0_275:
	s_waitcnt lgkmcnt(0)
	s_barrier
	s_cmp_lt_i32 s4, 1
	s_cbranch_scc1 .LBB0_283
	v_and_b32_e32 v0, 0x5f, v74
	v_mul_u32_u24_e32 v202, 0x90, v0
	v_lshrrev_b32_e32 v0, 1, v74
	v_and_b32_e32 v66, 31, v74
	v_and_b32_e32 v203, 16, v0
	v_and_or_b32 v0, v0, s88, v66
	v_mov_b32_e32 v66, 0
	v_mul_lo_u32 v204, v0, s87
	v_or_b32_e32 v0, 0x80, v75
	s_mov_b32 s5, 0
	v_mov_b32_e32 v67, v66
	v_mov_b64_e32 v[68:69], v[66:67]
	v_mov_b64_e32 v[70:71], v[66:67]
	v_mov_b64_e32 v[72:73], v[66:67]
	v_mov_b64_e32 v[74:75], v[66:67]
	v_mov_b64_e32 v[76:77], v[66:67]
	v_mov_b64_e32 v[78:79], v[66:67]
	v_mov_b64_e32 v[80:81], v[66:67]
	v_mov_b64_e32 v[82:83], v[66:67]
	v_mov_b64_e32 v[84:85], v[66:67]
	v_mov_b64_e32 v[86:87], v[66:67]
	v_mov_b64_e32 v[88:89], v[66:67]
	v_mov_b64_e32 v[90:91], v[66:67]
	v_mov_b64_e32 v[92:93], v[66:67]
	v_mov_b64_e32 v[94:95], v[66:67]
	v_mov_b64_e32 v[96:97], v[66:67]
	v_mov_b64_e32 v[98:99], v[66:67]
	v_mov_b64_e32 v[100:101], v[66:67]
	v_mov_b64_e32 v[102:103], v[66:67]
	v_mov_b64_e32 v[104:105], v[66:67]
	v_mov_b64_e32 v[106:107], v[66:67]
	v_mov_b64_e32 v[108:109], v[66:67]
	v_mov_b64_e32 v[110:111], v[66:67]
	v_mov_b64_e32 v[112:113], v[66:67]
	v_mov_b64_e32 v[114:115], v[66:67]
	v_mov_b64_e32 v[116:117], v[66:67]
	v_mov_b64_e32 v[118:119], v[66:67]
	v_mov_b64_e32 v[120:121], v[66:67]
	v_mov_b64_e32 v[122:123], v[66:67]
	v_mov_b64_e32 v[124:125], v[66:67]
	v_mov_b64_e32 v[126:127], v[66:67]
	v_mov_b64_e32 v[128:129], v[66:67]

.LBB0_347:
	s_waitcnt lgkmcnt(0)
	s_barrier
	s_cmp_lt_i32 s1, 1
	s_cbranch_scc1 .LBB0_355
	v_and_b32_e32 v0, 31, v10
	v_lshrrev_b32_e32 v2, 1, v10
	v_and_or_b32 v3, v2, s88, v0
	v_and_b32_e32 v248, 16, v2
	v_lshlrev_b32_e32 v2, 1, v10
	s_movk_i32 s2, 0x80
	v_and_or_b32 v0, v2, s2, v0
	v_mov_b32_e32 v2, 0
	v_mul_lo_u32 v247, v3, s87
	v_mul_u32_u24_e32 v249, 0x90, v0
	v_or_b32_e32 v0, 0x80, v11
	s_mov_b32 s2, 0
	v_mov_b32_e32 v3, v2
	v_mov_b64_e32 v[4:5], v[2:3]
	v_mov_b64_e32 v[6:7], v[2:3]
	v_mov_b64_e32 v[8:9], v[2:3]
	v_mov_b64_e32 v[10:11], v[2:3]
	v_mov_b64_e32 v[12:13], v[2:3]
	v_mov_b64_e32 v[14:15], v[2:3]
	v_mov_b64_e32 v[16:17], v[2:3]
	v_mov_b64_e32 v[18:19], v[2:3]
	v_mov_b64_e32 v[20:21], v[2:3]
	v_mov_b64_e32 v[22:23], v[2:3]
	v_mov_b64_e32 v[24:25], v[2:3]
	v_mov_b64_e32 v[26:27], v[2:3]
	v_mov_b64_e32 v[28:29], v[2:3]
	v_mov_b64_e32 v[30:31], v[2:3]
	v_mov_b64_e32 v[32:33], v[2:3]
	v_mov_b64_e32 v[34:35], v[2:3]
	v_mov_b64_e32 v[36:37], v[2:3]
	v_mov_b64_e32 v[38:39], v[2:3]
	v_mov_b64_e32 v[40:41], v[2:3]
	v_mov_b64_e32 v[42:43], v[2:3]
	v_mov_b64_e32 v[44:45], v[2:3]
	v_mov_b64_e32 v[46:47], v[2:3]
	v_mov_b64_e32 v[48:49], v[2:3]
	v_mov_b64_e32 v[50:51], v[2:3]
	v_mov_b64_e32 v[52:53], v[2:3]
	v_mov_b64_e32 v[54:55], v[2:3]
	v_mov_b64_e32 v[56:57], v[2:3]
	v_mov_b64_e32 v[58:59], v[2:3]
	v_mov_b64_e32 v[60:61], v[2:3]
	v_mov_b64_e32 v[62:63], v[2:3]
	v_mov_b64_e32 v[64:65], v[2:3]
	v_mov_b64_e32 v[66:67], v[2:3]
	v_mov_b64_e32 v[68:69], v[2:3]
	v_mov_b64_e32 v[70:71], v[2:3]
	v_mov_b64_e32 v[72:73], v[2:3]
	v_mov_b64_e32 v[74:75], v[2:3]
	v_mov_b64_e32 v[76:77], v[2:3]
	v_mov_b64_e32 v[78:79], v[2:3]
	v_mov_b64_e32 v[80:81], v[2:3]
	v_mov_b64_e32 v[82:83], v[2:3]
	v_mov_b64_e32 v[84:85], v[2:3]
	v_mov_b64_e32 v[86:87], v[2:3]
	v_mov_b64_e32 v[88:89], v[2:3]
	v_mov_b64_e32 v[90:91], v[2:3]
	v_mov_b64_e32 v[92:93], v[2:3]
	v_mov_b64_e32 v[94:95], v[2:3]
	v_mov_b64_e32 v[96:97], v[2:3]
	v_mov_b64_e32 v[98:99], v[2:3]
	v_mov_b64_e32 v[100:101], v[2:3]
	v_mov_b64_e32 v[102:103], v[2:3]
	v_mov_b64_e32 v[104:105], v[2:3]
	v_mov_b64_e32 v[106:107], v[2:3]
	v_mov_b64_e32 v[108:109], v[2:3]
	v_mov_b64_e32 v[110:111], v[2:3]
	v_mov_b64_e32 v[112:113], v[2:3]
	v_mov_b64_e32 v[114:115], v[2:3]
	v_mov_b64_e32 v[116:117], v[2:3]
	v_mov_b64_e32 v[118:119], v[2:3]
	v_mov_b64_e32 v[120:121], v[2:3]
	v_mov_b64_e32 v[122:123], v[2:3]
	v_mov_b64_e32 v[124:125], v[2:3]
	v_mov_b64_e32 v[126:127], v[2:3]
	v_mov_b64_e32 v[128:129], v[2:3]
